# ATTN prompt-unit K/V staging: all 8 global loads issued before one wait and 8 ds_writes (was 4 serialized load-wait-write rounds)
# baseline (speedup 1.0000x reference)
; #define LAS __attribute__((address_space(3)))
; __device__ __forceinline__ void attn_phase(const Ctx& c, int mode) {
;     ...
; #pragma unroll
;         for (int i = 0; i < 4; ++i) {
;             const int idx = tid + 512 * i, j = idx >> 3, cc = idx & 7;
;             u32x4 kv = (u32x4){0u, 0u, 0u, 0u}, vv = kv;
;             if (qb > 0 || j >= 128) { const bf16_t* rp = QKV + (krow0 + j) * QKVD + g * 64 + cc * 8; kv = *(const u32x4*)(rp + 1024); vv = *(const u32x4*)(rp + 1280); }
;             *(LAS u32x4*)(lds + AT_K + j * AT_KROW + cc * 16) = kv;
;             *(LAS u32x4*)(lds + AT_V + j * AT_VROW + cc * 16) = vv;
;         }
;         const int hh = 4 * g + (w >> 1);
;         const float sinkv = sinks[hh];
;         const size_t qrow0 = (size_t)b * PSEQ + (size_t)qb * 128;
;         const int lq = c.lane >> 4, lc = c.lane & 15;
;         const bf16_t* qp = QKV + (qrow0 + (w & 1) * 64 + lc) * QKVD + hh * 64 + 8 * lq;
;         bf16x8 qn[2];
; #pragma unroll
;         for (int k = 0; k < 2; ++k) qn[k] = *(const bf16x8*)(qp + 32 * k);
;         float bm[9][4];
;         attn_bias(bm, (const LAS float*)(lds + AT_BT) + hh * 132, lc, lq);
;         __syncthreads();
.LBB0_29:
	s_or_b64 exec, exec, s[22:23]
	s_lshl_b32 s20, s60, 2
	s_add_i32 s20, s20, s27
	s_ashr_i32 s21, s20, 31
	s_lshl_b64 s[22:23], s[20:21], 2
	v_readlane_b32 s60, v251, 63
	v_readlane_b32 s61, v252, 0
	s_add_u32 s22, s60, s22
	s_addc_u32 s23, s61, s23
	v_or_b32_e32 v3, s54, v32
	v_mov_b64_e32 v[0:1], s[14:15]
	s_movk_i32 s60, 0xc00
	global_load_dword v127, v2, s[22:23]
	v_mad_u64_u32 v[0:1], s[22:23], v3, s60, v[0:1]
	s_mul_i32 s21, s55, 0xc00
	s_lshl_b32 s22, s20, 6
	v_add_u32_e32 v1, s21, v1
	s_ashr_i32 s23, s22, 31
	v_lshl_add_u64 v[0:1], s[22:23], 1, v[0:1]
	v_mov_b32_e32 v39, v2
	v_lshl_add_u64 v[0:1], v[0:1], 0, v[38:39]
	global_load_dwordx4 v[16:19], v[0:1], off
	global_load_dwordx4 v[12:15], v[0:1], off offset:64
	s_mulk_i32 s20, 0x210
	s_add_i32 s20, s20, 0
	s_add_i32 s20, s20, 0x12000
	s_waitcnt vmcnt(3)
	ds_write_b128 v123, v[40:43]
	ds_write_b128 v123, v[44:47] offset:36864
	ds_write_b128 v124, v[48:51]
	ds_write_b128 v124, v[52:55] offset:36864
	ds_write_b128 v125, v[56:59]
	ds_write_b128 v125, v[60:63] offset:36864
	ds_write_b128 v126, v[8:11]
	ds_write_b128 v126, v[4:7] offset:36864
	v_lshl_add_u32 v0, v75, 2, s20
	v_lshl_add_u32 v1, v100, 2, s20
	v_lshl_add_u32 v3, v101, 2, s20
	v_lshl_add_u32 v4, v102, 2, s20
	v_lshl_add_u32 v5, v103, 2, s20
	ds_read_b32 v0, v0
	ds_read_b32 v1, v1
	ds_read_b32 v3, v3
	ds_read_b32 v4, v4
	ds_read2_b32 v[40:41], v5 offset1:1
	v_lshl_add_u32 v5, v104, 2, s20
	v_lshl_add_u32 v6, v105, 2, s20
	v_lshl_add_u32 v7, v106, 2, s20
	v_lshl_add_u32 v8, v107, 2, s20
	ds_read2_b32 v[42:43], v5 offset1:1
	ds_read2_b32 v[44:45], v6 offset1:1
	ds_read2_b32 v[46:47], v7 offset1:1
	ds_read2_b32 v[48:49], v8 offset1:1
	v_lshl_add_u32 v5, v108, 2, s20
	v_lshl_add_u32 v6, v109, 2, s20
	v_lshl_add_u32 v7, v110, 2, s20
	v_lshl_add_u32 v8, v111, 2, s20
	ds_read2_b32 v[50:51], v5 offset1:1
	ds_read2_b32 v[52:53], v6 offset1:1
	ds_read2_b32 v[54:55], v7 offset1:1
	ds_read2_b32 v[56:57], v8 offset1:1
	v_lshl_add_u32 v5, v112, 2, s20
	v_lshl_add_u32 v6, v113, 2, s20
	v_lshl_add_u32 v7, v114, 2, s20
	v_lshl_add_u32 v8, v115, 2, s20
	ds_read2_b32 v[58:59], v5 offset1:1
	ds_read2_b32 v[60:61], v6 offset1:1
	ds_read2_b32 v[62:63], v7 offset1:1
	ds_read2_b32 v[64:65], v8 offset1:1
	v_lshl_add_u32 v5, v116, 2, s20
	v_lshl_add_u32 v6, v117, 2, s20
	v_lshl_add_u32 v7, v118, 2, s20
	v_lshl_add_u32 v8, v119, 2, s20
	v_lshl_add_u32 v9, v120, 2, s20
	ds_read2_b32 v[66:67], v5 offset1:1
	ds_read_b32 v5, v6
	ds_read_b32 v6, v7
	ds_read_b32 v7, v8
	ds_read_b32 v8, v9
	s_andn2_b64 vcc, exec, s[16:17]
	v_readlane_b32 s62, v252, 1
	v_readlane_b32 s63, v252, 2
	v_readlane_b32 s64, v252, 3
	v_readlane_b32 s65, v252, 4
	v_readlane_b32 s66, v252, 5
	v_readlane_b32 s67, v252, 6
	s_waitcnt lgkmcnt(0)
	s_barrier
	s_cbranch_vccz .LBB0_39

; #define LAS __attribute__((address_space(3)))
; __device__ __forceinline__ void attn_phase(const Ctx& c, int mode) {
;     ...
;     for (int u = c.bid; u < (mode == 2 ? 0 : 1024); u += c.G) {
;         const int b = u >> 7, qb = (u >> 2) & 31, g = u & 3;
;         const size_t krow0 = (size_t)b * PSEQ + (size_t)qb * 128 - 128;
; #pragma unroll
;         for (int i = 0; i < 4; ++i) {
;             const int idx = tid + 512 * i, j = idx >> 3, cc = idx & 7;
;             u32x4 kv = (u32x4){0u, 0u, 0u, 0u}, vv = kv;
;             if (qb > 0 || j >= 128) { const bf16_t* rp = QKV + (krow0 + j) * QKVD + g * 64 + cc * 8; kv = *(const u32x4*)(rp + 1024); vv = *(const u32x4*)(rp + 1280); }
;             *(LAS u32x4*)(lds + AT_K + j * AT_KROW + cc * 16) = kv;
;             *(LAS u32x4*)(lds + AT_V + j * AT_VROW + cc * 16) = vv;
;         }
.LBB0_31:
	s_ashr_i32 s10, s58, 7
	s_bfe_u32 s59, s58, 0x50002
	s_ashr_i32 s11, s10, 31
	s_lshl_b64 s[18:19], s[10:11], 12
	s_lshl_b32 s20, s59, 7
	s_and_b32 s60, s58, 3
	s_or_b32 s54, s18, s20
	s_add_u32 s20, s54, 0xffffff80
	s_addc_u32 s21, s19, -1
	s_cmp_lg_u32 s59, 0
	s_cselect_b64 s[22:23], -1, 0
	s_lshl_b32 s34, s60, 7
	s_mov_b32 s55, s19
	v_lshl_add_u64 v[0:1], v[22:23], 0, s[34:35]
	s_or_b64 s[62:63], s[2:3], s[22:23]
	s_waitcnt vmcnt(0)
	v_mov_b32_e32 v4, 0
	v_mov_b32_e32 v5, 0
	v_mov_b32_e32 v6, 0
	v_mov_b32_e32 v7, 0
	v_mov_b32_e32 v8, 0
	v_mov_b32_e32 v9, 0
	v_mov_b32_e32 v10, 0
	v_mov_b32_e32 v11, 0
	v_mov_b32_e32 v40, 0
	v_mov_b32_e32 v41, 0
	v_mov_b32_e32 v42, 0
	v_mov_b32_e32 v43, 0
	v_mov_b32_e32 v44, 0
	v_mov_b32_e32 v45, 0
	v_mov_b32_e32 v46, 0
	v_mov_b32_e32 v47, 0
	v_mov_b32_e32 v48, 0
	v_mov_b32_e32 v49, 0
	v_mov_b32_e32 v50, 0
	v_mov_b32_e32 v51, 0
	v_mov_b32_e32 v52, 0
	v_mov_b32_e32 v53, 0
	v_mov_b32_e32 v54, 0
	v_mov_b32_e32 v55, 0
	v_mov_b32_e32 v56, 0
	v_mov_b32_e32 v57, 0
	v_mov_b32_e32 v58, 0
	v_mov_b32_e32 v59, 0
	v_mov_b32_e32 v60, 0
	v_mov_b32_e32 v61, 0
	v_mov_b32_e32 v62, 0
	v_mov_b32_e32 v63, 0
	s_and_saveexec_b64 s[24:25], s[62:63]
	s_cbranch_execz .Lat_r1
	v_lshl_add_u64 v[6:7], s[20:21], 0, v[24:25]
	s_movk_i32 s34, 0xc00
	v_mad_u64_u32 v[8:9], s[62:63], v6, s34, v[0:1]
	v_mov_b32_e32 v6, v9
	v_mad_u64_u32 v[6:7], s[62:63], v7, s34, v[6:7]
	v_mov_b32_e32 v9, v6
	global_load_dwordx4 v[40:43], v[8:9], off offset:2048
	global_load_dwordx4 v[44:47], v[8:9], off offset:2560
.Lat_r1:
	s_or_b64 exec, exec, s[24:25]
	s_or_b64 s[62:63], s[22:23], s[4:5]
	s_and_saveexec_b64 s[24:25], s[62:63]
	s_cbranch_execz .Lat_r2
	v_lshl_add_u64 v[6:7], s[20:21], 0, v[26:27]
	s_movk_i32 s34, 0xc00
	v_mad_u64_u32 v[8:9], s[62:63], v6, s34, v[0:1]
	v_mov_b32_e32 v6, v9
	v_mad_u64_u32 v[6:7], s[62:63], v7, s34, v[6:7]
	v_mov_b32_e32 v9, v6
	global_load_dwordx4 v[48:51], v[8:9], off offset:2048
	global_load_dwordx4 v[52:55], v[8:9], off offset:2560
.Lat_r2:
	s_or_b64 exec, exec, s[24:25]
	s_or_b64 s[62:63], s[22:23], s[6:7]
	s_and_saveexec_b64 s[24:25], s[62:63]
	s_cbranch_execz .Lat_r3
	v_lshl_add_u64 v[12:13], s[20:21], 0, v[28:29]
	s_movk_i32 s34, 0xc00
	v_mad_u64_u32 v[14:15], s[62:63], v12, s34, v[0:1]
	v_mov_b32_e32 v12, v15
	v_mad_u64_u32 v[12:13], s[62:63], v13, s34, v[12:13]
	v_mov_b32_e32 v15, v12
	global_load_dwordx4 v[56:59], v[14:15], off offset:2048
	global_load_dwordx4 v[60:63], v[14:15], off offset:2560
.Lat_r3:
	s_or_b64 exec, exec, s[24:25]
	s_or_b64 s[24:25], s[22:23], s[8:9]
	v_mov_b32_e32 v4, 0
	v_mov_b32_e32 v5, 0
	v_mov_b32_e32 v6, 0
	v_mov_b32_e32 v7, 0
	v_mov_b32_e32 v8, 0
	v_mov_b32_e32 v9, 0
	v_mov_b32_e32 v10, 0
	v_mov_b32_e32 v11, 0
	s_and_saveexec_b64 s[22:23], s[24:25]
	s_cbranch_execz .LBB0_29
	v_lshl_add_u64 v[4:5], s[20:21], 0, v[30:31]
	s_movk_i32 s24, 0xc00
	v_mad_u64_u32 v[0:1], s[20:21], v4, s24, v[0:1]
	v_mov_b32_e32 v4, v1
	v_mad_u64_u32 v[4:5], s[20:21], v5, s24, v[4:5]
	v_mov_b32_e32 v1, v4
	global_load_dwordx4 v[8:11], v[0:1], off offset:2048
	global_load_dwordx4 v[4:7], v[0:1], off offset:2560
	s_branch .LBB0_29
